# final bf16 to f32 write-out loop: 8 loads in flight per wave with counted waits
# speedup vs baseline: 1.0019x; 1.0019x over previous
.LBB0_951:
	v_readlane_b32 s0, v255, 26
	v_readlane_b32 s1, v255, 27
	s_andn2_b64 vcc, exec, s[0:1]
	s_mov_b32 s35, 0x16000
	s_mov_b32 s54, 0xa000
	s_mov_b32 s55, 0xb000
	s_mov_b32 s56, 0x2a000
	s_mov_b32 s57, 0x2c000
	s_cbranch_vccnz .LBB0_957
	v_readlane_b32 s0, v255, 32
	s_cmp_eq_u32 s0, 0
	s_cbranch_scc0 .LBB0_957
	s_ashr_i32 s47, s46, 31
	s_lshl_b64 s[0:1], s[46:47], 9
	s_waitcnt lgkmcnt(0)
	v_mov_b64_e32 v[0:1], 0x1ffffff
	v_cmp_gt_u64_e32 vcc, s[0:1], v[0:1]
	s_cbranch_vccnz .LBB0_957
	s_ashr_i32 s45, s44, 31
	v_lshl_or_b32 v0, v246, 3, s0
	v_mov_b32_e32 v1, s1
	s_lshl_b64 s[0:1], s[44:45], 9
	s_lshl_b64 s[4:5], s[46:47], 11
	s_add_u32 s4, s50, s4
	v_lshlrev_b32_e32 v96, 5, v246
	s_addc_u32 s5, s51, s5
	v_lshl_add_u64 v[2:3], s[4:5], 0, v[96:97]
	s_lshl_b64 s[4:5], s[44:45], 11
	s_lshl_b64 s[6:7], s[46:47], 10
	s_add_u32 s6, s52, s6
	v_lshlrev_b32_e32 v96, 4, v246
	s_addc_u32 s7, s53, s7
	v_lshl_add_u64 v[2:3], v[2:3], 0, 16
	v_lshl_add_u64 v[4:5], s[6:7], 0, v[96:97]
	s_lshl_b64 s[24:25], s[44:45], 10
	s_mov_b64 s[6:7], 0
	s_mov_b32 s8, 4
.LBB0_955:
	global_load_dwordx4 v[6:9], v[4:5], off
	v_lshl_add_u64 v[4:5], v[4:5], 0, s[24:25]
	global_load_dwordx4 v[10:13], v[4:5], off
	v_lshl_add_u64 v[4:5], v[4:5], 0, s[24:25]
	global_load_dwordx4 v[14:17], v[4:5], off
	v_lshl_add_u64 v[4:5], v[4:5], 0, s[24:25]
	global_load_dwordx4 v[18:21], v[4:5], off
	v_lshl_add_u64 v[4:5], v[4:5], 0, s[24:25]
	global_load_dwordx4 v[22:25], v[4:5], off
	v_lshl_add_u64 v[4:5], v[4:5], 0, s[24:25]
	global_load_dwordx4 v[26:29], v[4:5], off
	v_lshl_add_u64 v[4:5], v[4:5], 0, s[24:25]
	global_load_dwordx4 v[30:33], v[4:5], off
	v_lshl_add_u64 v[4:5], v[4:5], 0, s[24:25]
	global_load_dwordx4 v[34:37], v[4:5], off
	v_lshl_add_u64 v[4:5], v[4:5], 0, s[24:25]
	s_waitcnt vmcnt(7)
	v_lshlrev_b32_e32 v100, 16, v6
	v_and_b32_e32 v101, 0xffff0000, v6
	v_lshlrev_b32_e32 v102, 16, v7
	v_and_b32_e32 v103, 0xffff0000, v7
	v_lshlrev_b32_e32 v104, 16, v8
	v_and_b32_e32 v105, 0xffff0000, v8
	v_lshlrev_b32_e32 v106, 16, v9
	v_and_b32_e32 v107, 0xffff0000, v9
	global_store_dwordx4 v[2:3], v[100:103], off offset:-16
	global_store_dwordx4 v[2:3], v[104:107], off
	v_lshl_add_u64 v[2:3], v[2:3], 0, s[4:5]
	s_waitcnt vmcnt(8)
	v_lshlrev_b32_e32 v108, 16, v10
	v_and_b32_e32 v109, 0xffff0000, v10
	v_lshlrev_b32_e32 v110, 16, v11
	v_and_b32_e32 v111, 0xffff0000, v11
	v_lshlrev_b32_e32 v112, 16, v12
	v_and_b32_e32 v113, 0xffff0000, v12
	v_lshlrev_b32_e32 v114, 16, v13
	v_and_b32_e32 v115, 0xffff0000, v13
	global_store_dwordx4 v[2:3], v[108:111], off offset:-16
	global_store_dwordx4 v[2:3], v[112:115], off
	v_lshl_add_u64 v[2:3], v[2:3], 0, s[4:5]
	s_waitcnt vmcnt(9)
	v_lshlrev_b32_e32 v116, 16, v14
	v_and_b32_e32 v117, 0xffff0000, v14
	v_lshlrev_b32_e32 v118, 16, v15
	v_and_b32_e32 v119, 0xffff0000, v15
	v_lshlrev_b32_e32 v120, 16, v16
	v_and_b32_e32 v121, 0xffff0000, v16
	v_lshlrev_b32_e32 v122, 16, v17
	v_and_b32_e32 v123, 0xffff0000, v17
	global_store_dwordx4 v[2:3], v[116:119], off offset:-16
	global_store_dwordx4 v[2:3], v[120:123], off
	v_lshl_add_u64 v[2:3], v[2:3], 0, s[4:5]
	s_waitcnt vmcnt(10)
	v_lshlrev_b32_e32 v124, 16, v18
	v_and_b32_e32 v125, 0xffff0000, v18
	v_lshlrev_b32_e32 v126, 16, v19
	v_and_b32_e32 v127, 0xffff0000, v19
	v_lshlrev_b32_e32 v128, 16, v20
	v_and_b32_e32 v129, 0xffff0000, v20
	v_lshlrev_b32_e32 v130, 16, v21
	v_and_b32_e32 v131, 0xffff0000, v21
	global_store_dwordx4 v[2:3], v[124:127], off offset:-16
	global_store_dwordx4 v[2:3], v[128:131], off
	v_lshl_add_u64 v[2:3], v[2:3], 0, s[4:5]
	s_waitcnt vmcnt(11)
	v_lshlrev_b32_e32 v132, 16, v22
	v_and_b32_e32 v133, 0xffff0000, v22
	v_lshlrev_b32_e32 v134, 16, v23
	v_and_b32_e32 v135, 0xffff0000, v23
	v_lshlrev_b32_e32 v136, 16, v24
	v_and_b32_e32 v137, 0xffff0000, v24
	v_lshlrev_b32_e32 v138, 16, v25
	v_and_b32_e32 v139, 0xffff0000, v25
	global_store_dwordx4 v[2:3], v[132:135], off offset:-16
	global_store_dwordx4 v[2:3], v[136:139], off
	v_lshl_add_u64 v[2:3], v[2:3], 0, s[4:5]
	s_waitcnt vmcnt(12)
	v_lshlrev_b32_e32 v140, 16, v26
	v_and_b32_e32 v141, 0xffff0000, v26
	v_lshlrev_b32_e32 v142, 16, v27
	v_and_b32_e32 v143, 0xffff0000, v27
	v_lshlrev_b32_e32 v144, 16, v28
	v_and_b32_e32 v145, 0xffff0000, v28
	v_lshlrev_b32_e32 v146, 16, v29
	v_and_b32_e32 v147, 0xffff0000, v29
	global_store_dwordx4 v[2:3], v[140:143], off offset:-16
	global_store_dwordx4 v[2:3], v[144:147], off
	v_lshl_add_u64 v[2:3], v[2:3], 0, s[4:5]
	s_waitcnt vmcnt(13)
	v_lshlrev_b32_e32 v148, 16, v30
	v_and_b32_e32 v149, 0xffff0000, v30
	v_lshlrev_b32_e32 v150, 16, v31
	v_and_b32_e32 v151, 0xffff0000, v31
	v_lshlrev_b32_e32 v152, 16, v32
	v_and_b32_e32 v153, 0xffff0000, v32
	v_lshlrev_b32_e32 v154, 16, v33
	v_and_b32_e32 v155, 0xffff0000, v33
	global_store_dwordx4 v[2:3], v[148:151], off offset:-16
	global_store_dwordx4 v[2:3], v[152:155], off
	v_lshl_add_u64 v[2:3], v[2:3], 0, s[4:5]
	s_waitcnt vmcnt(14)
	v_lshlrev_b32_e32 v156, 16, v34
	v_and_b32_e32 v157, 0xffff0000, v34
	v_lshlrev_b32_e32 v158, 16, v35
	v_and_b32_e32 v159, 0xffff0000, v35
	v_lshlrev_b32_e32 v160, 16, v36
	v_and_b32_e32 v161, 0xffff0000, v36
	v_lshlrev_b32_e32 v162, 16, v37
	v_and_b32_e32 v163, 0xffff0000, v37
	global_store_dwordx4 v[2:3], v[156:159], off offset:-16
	global_store_dwordx4 v[2:3], v[160:163], off
	v_lshl_add_u64 v[2:3], v[2:3], 0, s[4:5]
	s_sub_i32 s8, s8, 1
	s_cmp_lg_u32 s8, 0
	s_cbranch_scc1 .LBB0_955
